# grid barriers: kernarg loads and XCC id read issued before the workgroup barrier instead of after it
# baseline (speedup 1.0000x reference)
; __global__ void __launch_bounds__(NTH, 2) mega_kernel(Params p) {
;     ...
;   grid.sync();
.LBB0_188:
	v_lshrrev_b32_e32 v1, 20, v0
	v_lshrrev_b32_e32 v0, 10, v0
	v_or_b32_e32 v0, v0, v1
	s_movk_i32 s4, 0x3ff
	v_and_or_b32 v0, v0, s4, v220
	v_cmp_eq_u32_e64 s[72:73], 0, v0
	s_load_dwordx2 s[6:7], s[0:1], 0x158
	s_load_dword s8, s[0:1], 0x490
	s_getreg_b32 s9, hwreg(HW_REG_XCC_ID, 0, 4)
	s_waitcnt vmcnt(0) lgkmcnt(0)
	s_barrier
	s_and_saveexec_b64 s[4:5], s[72:73]
	s_cbranch_execz .LBB0_198
	v_mov_b32_e32 v0, 0
	v_mov_b32_e32 v1, 1
	s_lshl_b32 s9, s9, 2
	v_mov_b32_e32 v3, s9
	s_waitcnt lgkmcnt(0)
	global_atomic_add v2, v3, v1, s[6:7] offset:160 sc0
	global_load_dword v3, v3, s[6:7] offset:192 sc1
	s_mul_i32 s8, s8, 1
	s_waitcnt vmcnt(0)
	v_add_u32_e32 v2, 1, v2
	v_mul_u32_u24_e32 v1, 1, v3
	v_cmp_ne_u32_e32 vcc, v1, v2
	s_cbranch_vccnz .Lgs1_wait
	buffer_wbl2 sc1
	s_waitcnt vmcnt(0)
	global_atomic_add v0, v3, s[6:7] offset:136

; #define RUNPH(k, call) for (int rep_ = 0; rep_ < (((REPMASK) >> (k)) & 1) + 1; ++rep_) { call; grid.sync(); }
; __global__ void __launch_bounds__(NTH, 2) mega_kernel(Params p) {
;     ...
;   RUNPH(2, phase2(p, smem))
.LBB0_302:
	s_load_dwordx2 s[6:7], s[0:1], 0x158
	s_load_dword s8, s[0:1], 0x490
	s_getreg_b32 s9, hwreg(HW_REG_XCC_ID, 0, 4)
	s_waitcnt vmcnt(0) lgkmcnt(0)
	s_barrier
	s_and_saveexec_b64 s[4:5], s[72:73]
	s_cbranch_execz .LBB0_312
	v_mov_b32_e32 v0, 0
	v_mov_b32_e32 v1, 1
	s_lshl_b32 s9, s9, 2
	v_mov_b32_e32 v3, s9
	s_waitcnt lgkmcnt(0)
	global_atomic_add v2, v3, v1, s[6:7] offset:160 sc0
	global_load_dword v3, v3, s[6:7] offset:192 sc1
	s_mul_i32 s8, s8, 2
	s_waitcnt vmcnt(0)
	v_add_u32_e32 v2, 1, v2
	v_mul_u32_u24_e32 v1, 2, v3
	v_cmp_ne_u32_e32 vcc, v1, v2
	s_cbranch_vccnz .Lgs2_wait
	buffer_wbl2 sc1
	s_waitcnt vmcnt(0)
	global_atomic_add v0, v3, s[6:7] offset:136

; #define RUNPH(k, call) for (int rep_ = 0; rep_ < (((REPMASK) >> (k)) & 1) + 1; ++rep_) { call; grid.sync(); }
; __global__ void __launch_bounds__(NTH, 2) mega_kernel(Params p) {
;     ...
;   RUNPH(3, phase3(p, smem))
.LBB0_525:
	s_load_dwordx2 s[6:7], s[0:1], 0x158
	s_load_dword s8, s[0:1], 0x490
	s_getreg_b32 s9, hwreg(HW_REG_XCC_ID, 0, 4)
	s_waitcnt vmcnt(0) lgkmcnt(0)
	s_barrier
	s_and_saveexec_b64 s[4:5], s[72:73]
	s_cbranch_execz .LBB0_535
	v_mov_b32_e32 v0, 0
	v_mov_b32_e32 v1, 1
	s_lshl_b32 s9, s9, 2
	v_mov_b32_e32 v3, s9
	s_waitcnt lgkmcnt(0)
	global_atomic_add v2, v3, v1, s[6:7] offset:160 sc0
	global_load_dword v3, v3, s[6:7] offset:192 sc1
	s_mul_i32 s8, s8, 3
	s_waitcnt vmcnt(0)
	v_add_u32_e32 v2, 1, v2
	v_mul_u32_u24_e32 v1, 3, v3
	v_cmp_ne_u32_e32 vcc, v1, v2
	s_cbranch_vccnz .Lgs3_wait
	buffer_wbl2 sc1
	s_waitcnt vmcnt(0)
	global_atomic_add v0, v3, s[6:7] offset:136

; #define RUNPH(k, call) for (int rep_ = 0; rep_ < (((REPMASK) >> (k)) & 1) + 1; ++rep_) { call; grid.sync(); }
; __global__ void __launch_bounds__(NTH, 2) mega_kernel(Params p) {
;     ...
;   RUNPH(4, phase4(p, smem))
.LBB0_645:
	s_load_dwordx2 s[6:7], s[0:1], 0x158
	s_load_dword s8, s[0:1], 0x490
	s_getreg_b32 s9, hwreg(HW_REG_XCC_ID, 0, 4)
	s_waitcnt vmcnt(0) lgkmcnt(0)
	s_barrier
	s_and_saveexec_b64 s[4:5], s[72:73]
	s_cbranch_execz .LBB0_655
	v_mov_b32_e32 v0, 0
	v_mov_b32_e32 v1, 1
	s_lshl_b32 s9, s9, 2
	v_mov_b32_e32 v3, s9
	s_waitcnt lgkmcnt(0)
	global_atomic_add v2, v3, v1, s[6:7] offset:160 sc0
	global_load_dword v3, v3, s[6:7] offset:192 sc1
	s_mul_i32 s8, s8, 4
	s_waitcnt vmcnt(0)
	v_add_u32_e32 v2, 1, v2
	v_mul_u32_u24_e32 v1, 4, v3
	v_cmp_ne_u32_e32 vcc, v1, v2
	s_cbranch_vccnz .Lgs4_wait
	buffer_wbl2 sc1
	s_waitcnt vmcnt(0)
	global_atomic_add v0, v3, s[6:7] offset:136

; #define RUNPH(k, call) for (int rep_ = 0; rep_ < (((REPMASK) >> (k)) & 1) + 1; ++rep_) { call; grid.sync(); }
; __global__ void __launch_bounds__(NTH, 2) mega_kernel(Params p) {
;     ...
;   RUNPH(5, phase5(p, smem))
.LBB0_882:
	s_load_dwordx2 s[6:7], s[0:1], 0x158
	s_load_dword s8, s[0:1], 0x490
	s_getreg_b32 s9, hwreg(HW_REG_XCC_ID, 0, 4)
	s_waitcnt vmcnt(0) lgkmcnt(0)
	s_barrier
	s_and_saveexec_b64 s[4:5], s[72:73]
	s_cbranch_execz .LBB0_892
	v_mov_b32_e32 v0, 0
	v_mov_b32_e32 v1, 1
	s_lshl_b32 s9, s9, 2
	v_mov_b32_e32 v3, s9
	s_waitcnt lgkmcnt(0)
	global_atomic_add v2, v3, v1, s[6:7] offset:160 sc0
	global_load_dword v3, v3, s[6:7] offset:192 sc1
	s_mul_i32 s8, s8, 5
	s_waitcnt vmcnt(0)
	v_add_u32_e32 v2, 1, v2
	v_mul_u32_u24_e32 v1, 5, v3
	v_cmp_ne_u32_e32 vcc, v1, v2
	s_cbranch_vccnz .Lgs5_wait
	buffer_wbl2 sc1
	s_waitcnt vmcnt(0)
	global_atomic_add v0, v3, s[6:7] offset:136

; #define RUNPH(k, call) for (int rep_ = 0; rep_ < (((REPMASK) >> (k)) & 1) + 1; ++rep_) { call; grid.sync(); }
; __global__ void __launch_bounds__(NTH, 2) mega_kernel(Params p) {
;     ...
;   RUNPH(6, phase6(p, smem))
.LBB0_929:
	s_load_dwordx2 s[6:7], s[0:1], 0x158
	s_load_dword s8, s[0:1], 0x490
	s_getreg_b32 s9, hwreg(HW_REG_XCC_ID, 0, 4)
	s_waitcnt vmcnt(0) lgkmcnt(0)
	s_barrier
	s_and_saveexec_b64 s[4:5], s[72:73]
	s_cbranch_execz .LBB0_939
	v_mov_b32_e32 v0, 0
	v_mov_b32_e32 v1, 1
	s_lshl_b32 s9, s9, 2
	v_mov_b32_e32 v3, s9
	s_waitcnt lgkmcnt(0)
	global_atomic_add v2, v3, v1, s[6:7] offset:160 sc0
	global_load_dword v3, v3, s[6:7] offset:192 sc1
	s_mul_i32 s8, s8, 6
	s_waitcnt vmcnt(0)
	v_add_u32_e32 v2, 1, v2
	v_mul_u32_u24_e32 v1, 6, v3
	v_cmp_ne_u32_e32 vcc, v1, v2
	s_cbranch_vccnz .Lgs6_wait
	buffer_wbl2 sc1
	s_waitcnt vmcnt(0)
	global_atomic_add v0, v3, s[6:7] offset:136

; #define RUNPH(k, call) for (int rep_ = 0; rep_ < (((REPMASK) >> (k)) & 1) + 1; ++rep_) { call; grid.sync(); }
; __global__ void __launch_bounds__(NTH, 2) mega_kernel(Params p) {
;     ...
;   RUNPH(7, phase7(p, smem))
.LBB0_968:
	s_or_b64 exec, exec, s[18:19]
	s_load_dwordx2 s[6:7], s[0:1], 0x158
	s_load_dword s8, s[0:1], 0x490
	s_getreg_b32 s9, hwreg(HW_REG_XCC_ID, 0, 4)
	s_waitcnt vmcnt(0) lgkmcnt(0)
	s_barrier
	s_and_saveexec_b64 s[4:5], s[72:73]
	s_cbranch_execz .LBB0_978
	v_mov_b32_e32 v0, 0
	v_mov_b32_e32 v1, 1
	s_lshl_b32 s9, s9, 2
	v_mov_b32_e32 v3, s9
	s_waitcnt lgkmcnt(0)
	global_atomic_add v2, v3, v1, s[6:7] offset:160 sc0
	global_load_dword v3, v3, s[6:7] offset:192 sc1
	s_mul_i32 s8, s8, 7
	s_waitcnt vmcnt(0)
	v_add_u32_e32 v2, 1, v2
	v_mul_u32_u24_e32 v1, 7, v3
	v_cmp_ne_u32_e32 vcc, v1, v2
	s_cbranch_vccnz .Lgs7_wait
	buffer_wbl2 sc1
	s_waitcnt vmcnt(0)
	global_atomic_add v0, v3, s[6:7] offset:136

; #define RUNPH(k, call) for (int rep_ = 0; rep_ < (((REPMASK) >> (k)) & 1) + 1; ++rep_) { call; grid.sync(); }
; __global__ void __launch_bounds__(NTH, 2) mega_kernel(Params p) {
;     ...
;   RUNPH(8, phase8(p))
.LBB0_1175:
	s_or_b64 exec, exec, s[88:89]
	s_load_dwordx2 s[6:7], s[0:1], 0x158
	s_load_dword s8, s[0:1], 0x490
	s_getreg_b32 s9, hwreg(HW_REG_XCC_ID, 0, 4)
	s_waitcnt vmcnt(0) lgkmcnt(0)
	s_barrier
	s_and_saveexec_b64 s[4:5], s[72:73]
	s_cbranch_execz .LBB0_1185
	v_mov_b32_e32 v0, 0
	v_mov_b32_e32 v1, 1
	s_lshl_b32 s9, s9, 2
	v_mov_b32_e32 v3, s9
	s_waitcnt lgkmcnt(0)
	global_atomic_add v2, v3, v1, s[6:7] offset:160 sc0
	global_load_dword v3, v3, s[6:7] offset:192 sc1
	s_mul_i32 s8, s8, 8
	s_waitcnt vmcnt(0)
	v_add_u32_e32 v2, 1, v2
	v_mul_u32_u24_e32 v1, 8, v3
	v_cmp_ne_u32_e32 vcc, v1, v2
	s_cbranch_vccnz .Lgs8_wait
	buffer_wbl2 sc1
	s_waitcnt vmcnt(0)
	global_atomic_add v0, v3, s[6:7] offset:136

; __global__ void __launch_bounds__(NTH, 2) mega_kernel(Params p) {
;     ...
;   grid.sync();
.LBB0_1372:
	s_load_dwordx2 s[6:7], s[0:1], 0x158
	s_load_dword s8, s[0:1], 0x490
	s_getreg_b32 s9, hwreg(HW_REG_XCC_ID, 0, 4)
	s_waitcnt vmcnt(0) lgkmcnt(0)
	s_barrier
	s_and_saveexec_b64 s[2:3], s[72:73]
	s_cbranch_execz .LBB0_1382
	v_mov_b32_e32 v0, 0
	v_mov_b32_e32 v1, 1
	s_lshl_b32 s9, s9, 2
	v_mov_b32_e32 v3, s9
	s_waitcnt lgkmcnt(0)
	global_atomic_add v2, v3, v1, s[6:7] offset:160 sc0
	global_load_dword v3, v3, s[6:7] offset:192 sc1
	s_mul_i32 s8, s8, 9
	s_waitcnt vmcnt(0)
	v_add_u32_e32 v2, 1, v2
	v_mul_u32_u24_e32 v1, 9, v3
	v_cmp_ne_u32_e32 vcc, v1, v2
	s_cbranch_vccnz .Lgs9_wait
	buffer_wbl2 sc1
	s_waitcnt vmcnt(0)
	global_atomic_add v0, v3, s[6:7] offset:136
